# prep row-loop latch: counted vmcnt(9) on the store-only paths (boundary paths keep their drain); LayerNorm second-FFN variant: last bf16 store waits vmcnt(3) instead of 0
# baseline (speedup 1.0000x reference)
.LBB0_561:
	s_mov_b64 s[12:13], 0x630
	v_lshl_add_u64 v[124:125], v[124:125], 0, s[12:13]
	v_lshl_add_u64 v[126:127], v[126:127], 0, s[12:13]
	v_lshl_add_u64 v[128:129], v[128:129], 0, s[12:13]
	v_lshl_add_u64 v[130:131], v[130:131], 0, s[12:13]
	s_mov_b64 s[12:13], 0xd00
	s_add_u32 s20, s20, 0x2000
	s_waitcnt vmcnt(9)
	v_mov_b32_e32 v56, v36
	v_mov_b32_e32 v57, v37
	v_mov_b32_e32 v58, v38
	v_mov_b32_e32 v59, v39
	v_mov_b32_e32 v36, v32
	v_mov_b32_e32 v37, v33
	v_mov_b32_e32 v38, v34
	v_mov_b32_e32 v39, v35
	v_mov_b32_e32 v32, v48
	v_mov_b32_e32 v33, v49
	v_mov_b32_e32 v34, v50
	v_mov_b32_e32 v35, v51
	v_mov_b64_e32 v[62:63], v[30:31]
	v_mov_b64_e32 v[50:51], v[26:27]
	v_mov_b64_e32 v[70:71], v[22:23]
	v_mov_b64_e32 v[66:67], v[18:19]
	v_lshl_add_u64 v[132:133], v[132:133], 0, s[12:13]
	v_lshl_add_u64 v[134:135], v[134:135], 0, s[12:13]
	v_lshl_add_u64 v[136:137], v[136:137], 0, s[96:97]
	v_lshl_add_u64 v[138:139], v[138:139], 0, s[96:97]
	v_lshl_add_u64 v[140:141], v[140:141], 0, s[96:97]
	v_lshl_add_u64 v[142:143], v[142:143], 0, s[96:97]
	s_addc_u32 s21, s21, 0
	v_lshl_add_u64 v[154:155], v[154:155], 0, s[96:97]
	s_andn2_b64 vcc, exec, s[22:23]
	s_mov_b32 s14, s38
	v_mov_b64_e32 v[90:91], v[156:157]
	v_mov_b64_e32 v[84:85], v[162:163]
	v_mov_b64_e32 v[88:89], v[160:161]
	v_mov_b64_e32 v[86:87], v[158:159]
	v_mov_b64_e32 v[82:83], v[164:165]
	v_mov_b64_e32 v[78:79], v[166:167]
	v_mov_b64_e32 v[76:77], v[172:173]
	v_mov_b64_e32 v[80:81], v[170:171]
	v_mov_b64_e32 v[96:97], v[168:169]
	v_mov_b32_e32 v92, v183
	v_mov_b32_e32 v187, v186
	v_mov_b32_e32 v184, v185
	v_mov_b64_e32 v[60:61], v[28:29]
	v_mov_b64_e32 v[48:49], v[24:25]
	v_mov_b64_e32 v[68:69], v[20:21]
	v_mov_b64_e32 v[64:65], v[16:17]
	v_mov_b64_e32 v[46:47], v[14:15]
	v_mov_b64_e32 v[14:15], v[10:11]
	v_mov_b64_e32 v[10:11], v[74:75]
	v_mov_b64_e32 v[44:45], v[12:13]
	v_mov_b64_e32 v[12:13], v[8:9]
	v_mov_b64_e32 v[8:9], v[72:73]
	v_mov_b64_e32 v[42:43], v[6:7]
	v_mov_b64_e32 v[6:7], v[2:3]
	v_mov_b64_e32 v[2:3], v[54:55]
	v_mov_b64_e32 v[40:41], v[4:5]
	v_mov_b64_e32 v[4:5], v[0:1]
	v_mov_b64_e32 v[0:1], v[52:53]
	s_cbranch_vccz .LBB0_627

.LBB0_618:
	s_and_b64 vcc, exec, s[14:15]
	s_waitcnt vmcnt(0)
	s_cbranch_vccz .LBB0_561
	s_branch .LBB0_626

.LBB0_623:
	v_mov_b32_e32 v36, 0
	s_and_b64 vcc, exec, s[12:13]
	v_mov_b32_e32 v37, 0
	v_mov_b32_e32 v38, 0
	v_mov_b32_e32 v39, 0
	s_cbranch_vccnz .LBB0_625
	global_load_dwordx4 v[36:39], v144, s[24:25] offset:2048
.LBB0_625:
	s_waitcnt vmcnt(0)
	s_branch .LBB0_561
.LBB0_626:
	s_waitcnt vmcnt(0)
	v_add_co_u32_e32 v36, vcc, 0x83fd000, v40
	s_nop 1
	v_addc_co_u32_e32 v37, vcc, 0, v41, vcc
	global_load_dwordx2 v[38:39], v[36:37], off offset:2592
	s_waitcnt vmcnt(0)
	v_lshlrev_b32_e32 v36, 16, v38
	v_and_b32_e32 v37, 0xffff0000, v38
	v_lshlrev_b32_e32 v38, 16, v39
	v_and_b32_e32 v39, 0xffff0000, v39
	s_waitcnt vmcnt(0)
	s_branch .LBB0_561

.LBB0_1464:
	s_and_b64 vcc, exec, s[8:9]
	s_cbranch_vccnz .LBB0_1436
	s_waitcnt vmcnt(3)
	v_pk_add_f32 v[102:103], v[60:61], 1.0 op_sel_hi:[1,0]
	v_pk_add_f32 v[100:101], v[62:63], 1.0 op_sel_hi:[1,0]
	v_pk_fma_f32 v[98:99], v[102:103], v[98:99], v[72:73]
	v_pk_fma_f32 v[96:97], v[100:101], v[96:97], v[74:75]
	v_cvt_pk_bf16_f32 v98, v98, v99
	s_nop 0
	v_cvt_pk_bf16_f32 v99, v96, v97
	global_store_dwordx2 v114, v[98:99], s[16:17] offset:1536
	s_branch .LBB0_1436
